# all eight GEMM main-loop heads and both phase-15 fast-path bodies aligned to 64 bytes (.p2align 6)
# baseline (speedup 1.0000x reference)
; template <class Epi>
; __device__ __forceinline__ void gemm_phase(LAS unsigned char* lds, const Gemm g, const StaticOrder& S, const Epi& E) {
;     ...
;     const bool has_next = S.next(ui + 1, nxt);
;     const char* nA = has_next ? (const char*)g.A + (size_t)nxt.pm * tstep : cA; const char* nB = has_next ? (const char*)g.Bt + (size_t)nxt.pn * tstep : cB;
;     for (int t = 0; t < nt; t += 2) {
;     ...
; #pragma unroll
;     for (int a = 0; a < 2; ++a)
; #pragma unroll
;       for (int b = 0; b < 2; ++b)
; #pragma unroll
;         for (int m = 0; m < 4; ++m)
; #pragma unroll
;           for (int n = 0; n < 2; ++n) acc[a][b][m][n] = (f32x4){0.f, 0.f, 0.f, 0.f};
;     cur = nxt; cA = nA; cB = nB; ++ui;
.LBB0_267:
	s_ashr_i32 s21, s20, 31
	v_cmp_lt_i64_e32 vcc, s[22:23], v[162:163]
	s_lshl_b64 s[22:23], s[20:21], 19
	s_add_u32 s22, s64, s22
	s_addc_u32 s23, s65, s23
	s_and_b64 s[24:25], vcc, exec
	s_cselect_b32 s21, s23, s27
	s_cselect_b32 s67, s22, s26
	s_ashr_i32 s19, s18, 31
	s_lshl_b64 s[24:25], s[18:19], 19
	s_add_u32 s24, s72, s24
	s_addc_u32 s25, s73, s25
	s_and_b64 s[34:35], vcc, exec
	s_cselect_b32 s19, s25, s39
	s_cselect_b32 s76, s24, s38
	s_add_u32 s26, s26, 0x40080
	s_addc_u32 s27, s27, 0
	s_add_u32 s77, s38, 0x100
	v_mov_b32_e32 v22, 0
	s_addc_u32 s78, s39, 0
	s_mov_b32 s34, -2
	v_mov_b32_e32 v23, v22
	v_mov_b32_e32 v24, v22
	v_mov_b32_e32 v25, v22
	v_mov_b32_e32 v26, v22
	v_mov_b32_e32 v27, v22
	v_mov_b32_e32 v28, v22
	v_mov_b32_e32 v29, v22
	v_mov_b32_e32 v30, v22
	v_mov_b32_e32 v31, v22
	v_mov_b32_e32 v32, v22
	v_mov_b32_e32 v33, v22
	v_mov_b32_e32 v38, v22
	v_mov_b32_e32 v39, v22
	v_mov_b32_e32 v40, v22
	v_mov_b32_e32 v41, v22
	v_mov_b32_e32 v46, v22
	v_mov_b32_e32 v47, v22
	v_mov_b32_e32 v48, v22
	v_mov_b32_e32 v49, v22
	v_mov_b32_e32 v54, v22
	v_mov_b32_e32 v55, v22
	v_mov_b32_e32 v56, v22
	v_mov_b32_e32 v57, v22
	v_mov_b32_e32 v62, v22
	v_mov_b32_e32 v63, v22
	v_mov_b32_e32 v64, v22
	v_mov_b32_e32 v65, v22
	v_mov_b32_e32 v70, v22
	v_mov_b32_e32 v71, v22
	v_mov_b32_e32 v72, v22
	v_mov_b32_e32 v73, v22
	v_mov_b32_e32 v34, v22
	v_mov_b32_e32 v35, v22
	v_mov_b32_e32 v36, v22
	v_mov_b32_e32 v37, v22
	v_mov_b32_e32 v42, v22
	v_mov_b32_e32 v43, v22
	v_mov_b32_e32 v44, v22
	v_mov_b32_e32 v45, v22
	v_mov_b32_e32 v50, v22
	v_mov_b32_e32 v51, v22
	v_mov_b32_e32 v52, v22
	v_mov_b32_e32 v53, v22
	v_mov_b32_e32 v58, v22
	v_mov_b32_e32 v59, v22
	v_mov_b32_e32 v60, v22
	v_mov_b32_e32 v61, v22
	v_mov_b32_e32 v66, v22
	v_mov_b32_e32 v67, v22
	v_mov_b32_e32 v68, v22
	v_mov_b32_e32 v69, v22
	v_mov_b32_e32 v74, v22
	v_mov_b32_e32 v75, v22
	v_mov_b32_e32 v76, v22
	v_mov_b32_e32 v77, v22
	v_mov_b32_e32 v78, v22
	v_mov_b32_e32 v79, v22
	v_mov_b32_e32 v80, v22
	v_mov_b32_e32 v81, v22
	v_mov_b32_e32 v82, v22
	v_mov_b32_e32 v83, v22
	v_mov_b32_e32 v84, v22
	v_mov_b32_e32 v85, v22
	v_mov_b32_e32 v86, v22
	v_mov_b32_e32 v87, v22
	v_mov_b32_e32 v88, v22
	v_mov_b32_e32 v89, v22
	v_mov_b32_e32 v90, v22
	v_mov_b32_e32 v91, v22
	v_mov_b32_e32 v92, v22
	v_mov_b32_e32 v93, v22
	v_mov_b32_e32 v94, v22
	v_mov_b32_e32 v95, v22
	v_mov_b32_e32 v96, v22
	v_mov_b32_e32 v97, v22
	v_mov_b32_e32 v102, v22
	v_mov_b32_e32 v103, v22
	v_mov_b32_e32 v104, v22
	v_mov_b32_e32 v105, v22
	v_mov_b32_e32 v110, v22
	v_mov_b32_e32 v111, v22
	v_mov_b32_e32 v112, v22
	v_mov_b32_e32 v113, v22
	v_mov_b32_e32 v118, v22
	v_mov_b32_e32 v119, v22
	v_mov_b32_e32 v120, v22
	v_mov_b32_e32 v121, v22
	v_mov_b32_e32 v126, v22
	v_mov_b32_e32 v127, v22
	v_mov_b32_e32 v128, v22
	v_mov_b32_e32 v129, v22
	v_mov_b32_e32 v134, v22
	v_mov_b32_e32 v135, v22
	v_mov_b32_e32 v136, v22
	v_mov_b32_e32 v137, v22
	v_mov_b32_e32 v98, v22
	v_mov_b32_e32 v99, v22
	v_mov_b32_e32 v100, v22
	v_mov_b32_e32 v101, v22
	v_mov_b32_e32 v106, v22
	v_mov_b32_e32 v107, v22
	v_mov_b32_e32 v108, v22
	v_mov_b32_e32 v109, v22
	v_mov_b32_e32 v114, v22
	v_mov_b32_e32 v115, v22
	v_mov_b32_e32 v116, v22
	v_mov_b32_e32 v117, v22
	v_mov_b32_e32 v122, v22
	v_mov_b32_e32 v123, v22
	v_mov_b32_e32 v124, v22
	v_mov_b32_e32 v125, v22
	v_mov_b32_e32 v130, v22
	v_mov_b32_e32 v131, v22
	v_mov_b32_e32 v132, v22
	v_mov_b32_e32 v133, v22
	v_mov_b32_e32 v138, v22
	v_mov_b32_e32 v139, v22
	v_mov_b32_e32 v140, v22
	v_mov_b32_e32 v141, v22
	v_mov_b32_e32 v142, v22
	v_mov_b32_e32 v143, v22
	v_mov_b32_e32 v144, v22
	v_mov_b32_e32 v145, v22
	v_mov_b32_e32 v146, v22
	v_mov_b32_e32 v147, v22
	v_mov_b32_e32 v148, v22
	v_mov_b32_e32 v149, v22
	.p2align 6

; template <class Epi>
; __device__ __forceinline__ void gemm_phase(LAS unsigned char* lds, const Gemm g, const StaticOrder& S, const Epi& E) {
;     ...
;     const bool has_next = S.next(ui + 1, nxt);
;     const char* nA = has_next ? (const char*)g.A + (size_t)nxt.pm * tstep : cA; const char* nB = has_next ? (const char*)g.Bt + (size_t)nxt.pn * tstep : cB;
;     for (int t = 0; t < nt; t += 2) {
;     ...
; #pragma unroll
;     for (int a = 0; a < 2; ++a)
; #pragma unroll
;       for (int b = 0; b < 2; ++b)
; #pragma unroll
;         for (int m = 0; m < 4; ++m)
; #pragma unroll
;           for (int n = 0; n < 2; ++n) acc[a][b][m][n] = (f32x4){0.f, 0.f, 0.f, 0.f};
;     cur = nxt; cA = nA; cB = nB; ++ui;
.LBB0_401:
	s_ashr_i32 s17, s16, 31
	v_cmp_lt_i64_e32 vcc, s[18:19], v[202:203]
	s_lshl_b64 s[18:19], s[16:17], 19
	s_add_u32 s18, s56, s18
	s_addc_u32 s19, s57, s19
	s_and_b64 s[20:21], vcc, exec
	s_cselect_b32 s17, s19, s27
	s_cselect_b32 s23, s18, s26
	s_ashr_i32 s11, s10, 31
	s_lshl_b64 s[20:21], s[10:11], 19
	s_add_u32 s20, s88, s20
	s_addc_u32 s21, s89, s21
	s_and_b64 s[34:35], vcc, exec
	s_cselect_b32 s11, s21, s39
	s_cselect_b32 s76, s20, s38
	s_add_u32 s26, s26, 0x40080
	s_addc_u32 s27, s27, 0
	s_add_u32 s77, s38, 0x100
	v_mov_b32_e32 v16, 0
	s_addc_u32 s78, s39, 0
	s_mov_b32 s34, -2
	s_waitcnt lgkmcnt(0)
	v_mov_b32_e32 v17, v16
	v_mov_b32_e32 v18, v16
	v_mov_b32_e32 v19, v16
	v_mov_b32_e32 v20, v16
	v_mov_b32_e32 v21, v16
	v_mov_b32_e32 v22, v16
	v_mov_b32_e32 v23, v16
	s_waitcnt vmcnt(0)
	v_mov_b32_e32 v32, v16
	v_mov_b32_e32 v33, v16
	v_mov_b32_e32 v34, v16
	v_mov_b32_e32 v35, v16
	v_mov_b32_e32 v36, v16
	v_mov_b32_e32 v37, v16
	v_mov_b32_e32 v38, v16
	v_mov_b32_e32 v39, v16
	v_mov_b32_e32 v48, v16
	v_mov_b32_e32 v49, v16
	v_mov_b32_e32 v50, v16
	v_mov_b32_e32 v51, v16
	v_mov_b32_e32 v52, v16
	v_mov_b32_e32 v53, v16
	v_mov_b32_e32 v54, v16
	v_mov_b32_e32 v55, v16
	v_mov_b32_e32 v64, v16
	v_mov_b32_e32 v65, v16
	v_mov_b32_e32 v66, v16
	v_mov_b32_e32 v67, v16
	v_mov_b32_e32 v68, v16
	v_mov_b32_e32 v69, v16
	v_mov_b32_e32 v70, v16
	v_mov_b32_e32 v71, v16
	v_mov_b32_e32 v24, v16
	v_mov_b32_e32 v25, v16
	v_mov_b32_e32 v26, v16
	v_mov_b32_e32 v27, v16
	v_mov_b32_e32 v28, v16
	v_mov_b32_e32 v29, v16
	v_mov_b32_e32 v30, v16
	v_mov_b32_e32 v31, v16
	v_mov_b32_e32 v40, v16
	v_mov_b32_e32 v41, v16
	v_mov_b32_e32 v42, v16
	v_mov_b32_e32 v43, v16
	v_mov_b32_e32 v44, v16
	v_mov_b32_e32 v45, v16
	v_mov_b32_e32 v46, v16
	v_mov_b32_e32 v47, v16
	v_mov_b32_e32 v56, v16
	v_mov_b32_e32 v57, v16
	v_mov_b32_e32 v58, v16
	v_mov_b32_e32 v59, v16
	v_mov_b32_e32 v60, v16
	v_mov_b32_e32 v61, v16
	v_mov_b32_e32 v62, v16
	v_mov_b32_e32 v63, v16
	v_mov_b32_e32 v72, v16
	v_mov_b32_e32 v73, v16
	v_mov_b32_e32 v74, v16
	v_mov_b32_e32 v75, v16
	v_mov_b32_e32 v76, v16
	v_mov_b32_e32 v77, v16
	v_mov_b32_e32 v78, v16
	v_mov_b32_e32 v79, v16
	v_mov_b32_e32 v80, v16
	v_mov_b32_e32 v81, v16
	v_mov_b32_e32 v82, v16
	v_mov_b32_e32 v83, v16
	v_mov_b32_e32 v84, v16
	v_mov_b32_e32 v85, v16
	v_mov_b32_e32 v86, v16
	v_mov_b32_e32 v87, v16
	v_mov_b32_e32 v96, v16
	v_mov_b32_e32 v97, v16
	v_mov_b32_e32 v98, v16
	v_mov_b32_e32 v99, v16
	v_mov_b32_e32 v100, v16
	v_mov_b32_e32 v101, v16
	v_mov_b32_e32 v102, v16
	v_mov_b32_e32 v103, v16
	v_mov_b32_e32 v112, v16
	v_mov_b32_e32 v113, v16
	v_mov_b32_e32 v114, v16
	v_mov_b32_e32 v115, v16
	v_mov_b32_e32 v116, v16
	v_mov_b32_e32 v117, v16
	v_mov_b32_e32 v118, v16
	v_mov_b32_e32 v119, v16
	v_mov_b32_e32 v128, v16
	v_mov_b32_e32 v129, v16
	v_mov_b32_e32 v130, v16
	v_mov_b32_e32 v131, v16
	v_mov_b32_e32 v132, v16
	v_mov_b32_e32 v133, v16
	v_mov_b32_e32 v134, v16
	v_mov_b32_e32 v135, v16
	v_mov_b32_e32 v88, v16
	v_mov_b32_e32 v89, v16
	v_mov_b32_e32 v90, v16
	v_mov_b32_e32 v91, v16
	v_mov_b32_e32 v92, v16
	v_mov_b32_e32 v93, v16
	v_mov_b32_e32 v94, v16
	v_mov_b32_e32 v95, v16
	v_mov_b32_e32 v104, v16
	v_mov_b32_e32 v105, v16
	v_mov_b32_e32 v106, v16
	v_mov_b32_e32 v107, v16
	v_mov_b32_e32 v108, v16
	v_mov_b32_e32 v109, v16
	v_mov_b32_e32 v110, v16
	v_mov_b32_e32 v111, v16
	v_mov_b32_e32 v120, v16
	v_mov_b32_e32 v121, v16
	v_mov_b32_e32 v122, v16
	v_mov_b32_e32 v123, v16
	v_mov_b32_e32 v124, v16
	v_mov_b32_e32 v125, v16
	v_mov_b32_e32 v126, v16
	v_mov_b32_e32 v127, v16
	v_mov_b32_e32 v136, v16
	v_mov_b32_e32 v137, v16
	v_mov_b32_e32 v138, v16
	v_mov_b32_e32 v139, v16
	v_mov_b32_e32 v140, v16
	v_mov_b32_e32 v141, v16
	v_mov_b32_e32 v142, v16
	v_mov_b32_e32 v143, v16
	.p2align 6

; template <class Epi>
; __device__ __forceinline__ void gemm_phase(LAS unsigned char* lds, const Gemm g, const StaticOrder& S, const Epi& E) {
;     ...
;     const bool has_next = S.next(ui + 1, nxt);
;     const char* nA = has_next ? (const char*)g.A + (size_t)nxt.pm * tstep : cA; const char* nB = has_next ? (const char*)g.Bt + (size_t)nxt.pn * tstep : cB;
;     for (int t = 0; t < nt; t += 2) {
;     ...
; #pragma unroll
;     for (int a = 0; a < 2; ++a)
; #pragma unroll
;       for (int b = 0; b < 2; ++b)
; #pragma unroll
;         for (int m = 0; m < 4; ++m)
; #pragma unroll
;           for (int n = 0; n < 2; ++n) acc[a][b][m][n] = (f32x4){0.f, 0.f, 0.f, 0.f};
;     cur = nxt; cA = nA; cB = nB; ++ui;
.LBB0_480:
	s_ashr_i32 s49, s48, 31
	s_lshl_b64 s[34:35], s[48:49], 19
	v_cmp_lt_i64_e32 vcc, s[50:51], v[184:185]
	s_add_u32 s50, s54, s34
	s_addc_u32 s51, s55, s35
	s_and_b64 s[34:35], vcc, exec
	s_cselect_b32 s39, s51, s61
	s_cselect_b32 s49, s50, s60
	s_ashr_i32 s47, s46, 31
	s_lshl_b64 s[34:35], s[46:47], 19
	v_readlane_b32 s12, v253, 18
	v_readlane_b32 s13, v253, 19
	s_add_u32 s58, s12, s34
	s_addc_u32 s59, s13, s35
	s_and_b64 s[34:35], vcc, exec
	s_cselect_b32 s47, s59, s67
	s_cselect_b32 vcc_lo, s58, s66
	s_add_u32 s60, s60, 0x40080
	s_addc_u32 s61, s61, 0
	s_add_u32 vcc_hi, s66, 0x100
	s_waitcnt vmcnt(0)
	v_mov_b32_e32 v32, 0
	s_addc_u32 s34, s67, 0
	s_mov_b32 s35, -2
	v_mov_b32_e32 v33, v32
	v_mov_b32_e32 v34, v32
	v_mov_b32_e32 v35, v32
	v_mov_b32_e32 v64, v32
	v_mov_b32_e32 v65, v32
	v_mov_b32_e32 v66, v32
	v_mov_b32_e32 v67, v32
	v_mov_b32_e32 v20, v32
	v_mov_b32_e32 v21, v32
	v_mov_b32_e32 v22, v32
	v_mov_b32_e32 v23, v32
	v_mov_b32_e32 v48, v32
	v_mov_b32_e32 v49, v32
	v_mov_b32_e32 v50, v32
	v_mov_b32_e32 v51, v32
	v_mov_b32_e32 v16, v32
	v_mov_b32_e32 v17, v32
	v_mov_b32_e32 v18, v32
	v_mov_b32_e32 v19, v32
	v_mov_b32_e32 v52, v32
	v_mov_b32_e32 v53, v32
	v_mov_b32_e32 v54, v32
	v_mov_b32_e32 v55, v32
	v_mov_b32_e32 v40, v32
	v_mov_b32_e32 v41, v32
	v_mov_b32_e32 v42, v32
	v_mov_b32_e32 v43, v32
	v_mov_b32_e32 v72, v32
	v_mov_b32_e32 v73, v32
	v_mov_b32_e32 v74, v32
	v_mov_b32_e32 v75, v32
	v_mov_b32_e32 v36, v32
	v_mov_b32_e32 v37, v32
	v_mov_b32_e32 v38, v32
	v_mov_b32_e32 v39, v32
	v_mov_b32_e32 v68, v32
	v_mov_b32_e32 v69, v32
	v_mov_b32_e32 v70, v32
	v_mov_b32_e32 v71, v32
	v_mov_b32_e32 v28, v32
	v_mov_b32_e32 v29, v32
	v_mov_b32_e32 v30, v32
	v_mov_b32_e32 v31, v32
	v_mov_b32_e32 v56, v32
	v_mov_b32_e32 v57, v32
	v_mov_b32_e32 v58, v32
	v_mov_b32_e32 v59, v32
	v_mov_b32_e32 v24, v32
	v_mov_b32_e32 v25, v32
	v_mov_b32_e32 v26, v32
	v_mov_b32_e32 v27, v32
	v_mov_b32_e32 v60, v32
	v_mov_b32_e32 v61, v32
	v_mov_b32_e32 v62, v32
	v_mov_b32_e32 v63, v32
	v_mov_b32_e32 v44, v32
	v_mov_b32_e32 v45, v32
	v_mov_b32_e32 v46, v32
	v_mov_b32_e32 v47, v32
	v_mov_b32_e32 v76, v32
	v_mov_b32_e32 v77, v32
	v_mov_b32_e32 v78, v32
	v_mov_b32_e32 v79, v32
	v_mov_b32_e32 v96, v32
	v_mov_b32_e32 v97, v32
	v_mov_b32_e32 v98, v32
	v_mov_b32_e32 v99, v32
	v_mov_b32_e32 v160, v32
	v_mov_b32_e32 v161, v32
	v_mov_b32_e32 v162, v32
	v_mov_b32_e32 v163, v32
	v_mov_b32_e32 v80, v32
	v_mov_b32_e32 v81, v32
	v_mov_b32_e32 v82, v32
	v_mov_b32_e32 v83, v32
	v_mov_b32_e32 v112, v32
	v_mov_b32_e32 v113, v32
	v_mov_b32_e32 v114, v32
	v_mov_b32_e32 v115, v32
	v_mov_b32_e32 v84, v32
	v_mov_b32_e32 v85, v32
	v_mov_b32_e32 v86, v32
	v_mov_b32_e32 v87, v32
	v_mov_b32_e32 v116, v32
	v_mov_b32_e32 v117, v32
	v_mov_b32_e32 v118, v32
	v_mov_b32_e32 v119, v32
	v_mov_b32_e32 v104, v32
	v_mov_b32_e32 v105, v32
	v_mov_b32_e32 v106, v32
	v_mov_b32_e32 v107, v32
	v_mov_b32_e32 v168, v32
	v_mov_b32_e32 v169, v32
	v_mov_b32_e32 v170, v32
	v_mov_b32_e32 v171, v32
	v_mov_b32_e32 v100, v32
	v_mov_b32_e32 v101, v32
	v_mov_b32_e32 v102, v32
	v_mov_b32_e32 v103, v32
	v_mov_b32_e32 v164, v32
	v_mov_b32_e32 v165, v32
	v_mov_b32_e32 v166, v32
	v_mov_b32_e32 v167, v32
	v_mov_b32_e32 v88, v32
	v_mov_b32_e32 v89, v32
	v_mov_b32_e32 v90, v32
	v_mov_b32_e32 v91, v32
	v_mov_b32_e32 v120, v32
	v_mov_b32_e32 v121, v32
	v_mov_b32_e32 v122, v32
	v_mov_b32_e32 v123, v32
	v_mov_b32_e32 v92, v32
	v_mov_b32_e32 v93, v32
	v_mov_b32_e32 v94, v32
	v_mov_b32_e32 v95, v32
	v_mov_b32_e32 v124, v32
	v_mov_b32_e32 v125, v32
	v_mov_b32_e32 v126, v32
	v_mov_b32_e32 v127, v32
	v_mov_b32_e32 v108, v32
	v_mov_b32_e32 v109, v32
	v_mov_b32_e32 v110, v32
	v_mov_b32_e32 v111, v32
	v_mov_b32_e32 v172, v32
	v_mov_b32_e32 v173, v32
	v_mov_b32_e32 v174, v32
	v_mov_b32_e32 v175, v32
	.p2align 6

; template <class Epi>
; __device__ __forceinline__ void gemm_phase(LAS unsigned char* lds, const Gemm g, const StaticOrder& S, const Epi& E) {
;     ...
;     const bool has_next = S.next(ui + 1, nxt);
;     const char* nA = has_next ? (const char*)g.A + (size_t)nxt.pm * tstep : cA; const char* nB = has_next ? (const char*)g.Bt + (size_t)nxt.pn * tstep : cB;
;     for (int t = 0; t < nt; t += 2) {
;     ...
; #pragma unroll
;     for (int a = 0; a < 2; ++a)
; #pragma unroll
;       for (int b = 0; b < 2; ++b)
; #pragma unroll
;         for (int m = 0; m < 4; ++m)
; #pragma unroll
;           for (int n = 0; n < 2; ++n) acc[a][b][m][n] = (f32x4){0.f, 0.f, 0.f, 0.f};
;     cur = nxt; cA = nA; cB = nB; ++ui;
.LBB0_628:
	s_add_u32 s18, s18, 0xb0080
	s_addc_u32 s19, s19, 0
	s_add_u32 s63, s20, 0x100
	v_mov_b32_e32 v16, 0
	s_addc_u32 s34, s21, 0
	s_mov_b32 s35, -2
	s_waitcnt lgkmcnt(0)
	v_mov_b32_e32 v17, v16
	v_mov_b32_e32 v18, v16
	v_mov_b32_e32 v19, v16
	v_mov_b32_e32 v20, v16
	v_mov_b32_e32 v21, v16
	v_mov_b32_e32 v22, v16
	v_mov_b32_e32 v23, v16
	s_waitcnt vmcnt(0)
	v_mov_b32_e32 v32, v16
	v_mov_b32_e32 v33, v16
	v_mov_b32_e32 v34, v16
	v_mov_b32_e32 v35, v16
	v_mov_b32_e32 v36, v16
	v_mov_b32_e32 v37, v16
	v_mov_b32_e32 v38, v16
	v_mov_b32_e32 v39, v16
	v_mov_b32_e32 v48, v16
	v_mov_b32_e32 v49, v16
	v_mov_b32_e32 v50, v16
	v_mov_b32_e32 v51, v16
	v_mov_b32_e32 v52, v16
	v_mov_b32_e32 v53, v16
	v_mov_b32_e32 v54, v16
	v_mov_b32_e32 v55, v16
	v_mov_b32_e32 v64, v16
	v_mov_b32_e32 v65, v16
	v_mov_b32_e32 v66, v16
	v_mov_b32_e32 v67, v16
	v_mov_b32_e32 v68, v16
	v_mov_b32_e32 v69, v16
	v_mov_b32_e32 v70, v16
	v_mov_b32_e32 v71, v16
	v_mov_b32_e32 v24, v16
	v_mov_b32_e32 v25, v16
	v_mov_b32_e32 v26, v16
	v_mov_b32_e32 v27, v16
	v_mov_b32_e32 v28, v16
	v_mov_b32_e32 v29, v16
	v_mov_b32_e32 v30, v16
	v_mov_b32_e32 v31, v16
	v_mov_b32_e32 v40, v16
	v_mov_b32_e32 v41, v16
	v_mov_b32_e32 v42, v16
	v_mov_b32_e32 v43, v16
	v_mov_b32_e32 v44, v16
	v_mov_b32_e32 v45, v16
	v_mov_b32_e32 v46, v16
	v_mov_b32_e32 v47, v16
	v_mov_b32_e32 v56, v16
	v_mov_b32_e32 v57, v16
	v_mov_b32_e32 v58, v16
	v_mov_b32_e32 v59, v16
	v_mov_b32_e32 v60, v16
	v_mov_b32_e32 v61, v16
	v_mov_b32_e32 v62, v16
	v_mov_b32_e32 v63, v16
	v_mov_b32_e32 v72, v16
	v_mov_b32_e32 v73, v16
	v_mov_b32_e32 v74, v16
	v_mov_b32_e32 v75, v16
	v_mov_b32_e32 v76, v16
	v_mov_b32_e32 v77, v16
	v_mov_b32_e32 v78, v16
	v_mov_b32_e32 v79, v16
	v_mov_b32_e32 v80, v16
	v_mov_b32_e32 v81, v16
	v_mov_b32_e32 v82, v16
	v_mov_b32_e32 v83, v16
	v_mov_b32_e32 v84, v16
	v_mov_b32_e32 v85, v16
	v_mov_b32_e32 v86, v16
	v_mov_b32_e32 v87, v16
	v_mov_b32_e32 v96, v16
	v_mov_b32_e32 v97, v16
	v_mov_b32_e32 v98, v16
	v_mov_b32_e32 v99, v16
	v_mov_b32_e32 v100, v16
	v_mov_b32_e32 v101, v16
	v_mov_b32_e32 v102, v16
	v_mov_b32_e32 v103, v16
	v_mov_b32_e32 v112, v16
	v_mov_b32_e32 v113, v16
	v_mov_b32_e32 v114, v16
	v_mov_b32_e32 v115, v16
	v_mov_b32_e32 v116, v16
	v_mov_b32_e32 v117, v16
	v_mov_b32_e32 v118, v16
	v_mov_b32_e32 v119, v16
	v_mov_b32_e32 v128, v16
	v_mov_b32_e32 v129, v16
	v_mov_b32_e32 v130, v16
	v_mov_b32_e32 v131, v16
	v_mov_b32_e32 v132, v16
	v_mov_b32_e32 v133, v16
	v_mov_b32_e32 v134, v16
	v_mov_b32_e32 v135, v16
	v_mov_b32_e32 v88, v16
	v_mov_b32_e32 v89, v16
	v_mov_b32_e32 v90, v16
	v_mov_b32_e32 v91, v16
	v_mov_b32_e32 v92, v16
	v_mov_b32_e32 v93, v16
	v_mov_b32_e32 v94, v16
	v_mov_b32_e32 v95, v16
	v_mov_b32_e32 v104, v16
	v_mov_b32_e32 v105, v16
	v_mov_b32_e32 v106, v16
	v_mov_b32_e32 v107, v16
	v_mov_b32_e32 v108, v16
	v_mov_b32_e32 v109, v16
	v_mov_b32_e32 v110, v16
	v_mov_b32_e32 v111, v16
	v_mov_b32_e32 v120, v16
	v_mov_b32_e32 v121, v16
	v_mov_b32_e32 v122, v16
	v_mov_b32_e32 v123, v16
	v_mov_b32_e32 v124, v16
	v_mov_b32_e32 v125, v16
	v_mov_b32_e32 v126, v16
	v_mov_b32_e32 v127, v16
	v_mov_b32_e32 v136, v16
	v_mov_b32_e32 v137, v16
	v_mov_b32_e32 v138, v16
	v_mov_b32_e32 v139, v16
	v_mov_b32_e32 v140, v16
	v_mov_b32_e32 v141, v16
	v_mov_b32_e32 v142, v16
	v_mov_b32_e32 v143, v16
	.p2align 6

; template <class Epi>
; __device__ __forceinline__ void gemm_phase(LAS unsigned char* lds, const Gemm g, const StaticOrder& S, const Epi& E) {
;     ...
;     const bool has_next = S.next(ui + 1, nxt);
;     const char* nA = has_next ? (const char*)g.A + (size_t)nxt.pm * tstep : cA; const char* nB = has_next ? (const char*)g.Bt + (size_t)nxt.pn * tstep : cB;
;     for (int t = 0; t < nt; t += 2) {
;     ...
; #pragma unroll
;     for (int a = 0; a < 2; ++a)
; #pragma unroll
;       for (int b = 0; b < 2; ++b)
; #pragma unroll
;         for (int m = 0; m < 4; ++m)
; #pragma unroll
;           for (int n = 0; n < 2; ++n) acc[a][b][m][n] = (f32x4){0.f, 0.f, 0.f, 0.f};
;     cur = nxt; cA = nA; cB = nB; ++ui;
.LBB0_711:
	s_ashr_i32 s45, s44, 31
	s_lshl_b64 s[34:35], s[44:45], 19
	s_add_u32 s50, s54, s34
	v_cmp_lt_i64_e32 vcc, s[38:39], v[170:171]
	s_addc_u32 s51, s55, s35
	s_and_b64 s[34:35], vcc, exec
	s_cselect_b32 s7, s51, s9
	s_cselect_b32 s18, s50, s8
	s_ashr_i32 s27, s26, 31
	s_lshl_b64 s[34:35], s[26:27], 19
	s_add_u32 s58, s42, s34
	s_addc_u32 s59, s43, s35
	s_and_b64 s[34:35], vcc, exec
	s_cselect_b32 s27, s59, s11
	s_cselect_b32 s40, s58, s10
	s_add_u32 s8, s8, 0x40080
	s_addc_u32 s9, s9, 0
	s_add_u32 s41, s10, 0x100
	v_mov_b32_e32 v20, 0
	s_addc_u32 s34, s11, 0
	s_mov_b32 s35, -2
	v_mov_b32_e32 v21, v20
	v_mov_b32_e32 v22, v20
	v_mov_b32_e32 v23, v20
	v_mov_b32_e32 v24, v20
	v_mov_b32_e32 v25, v20
	v_mov_b32_e32 v26, v20
	v_mov_b32_e32 v27, v20
	v_mov_b32_e32 v36, v20
	v_mov_b32_e32 v37, v20
	v_mov_b32_e32 v38, v20
	v_mov_b32_e32 v39, v20
	v_mov_b32_e32 v40, v20
	v_mov_b32_e32 v41, v20
	v_mov_b32_e32 v42, v20
	v_mov_b32_e32 v43, v20
	v_mov_b32_e32 v52, v20
	v_mov_b32_e32 v53, v20
	v_mov_b32_e32 v54, v20
	v_mov_b32_e32 v55, v20
	v_mov_b32_e32 v56, v20
	v_mov_b32_e32 v57, v20
	v_mov_b32_e32 v58, v20
	v_mov_b32_e32 v59, v20
	v_mov_b32_e32 v68, v20
	v_mov_b32_e32 v69, v20
	v_mov_b32_e32 v70, v20
	v_mov_b32_e32 v71, v20
	v_mov_b32_e32 v72, v20
	v_mov_b32_e32 v73, v20
	v_mov_b32_e32 v74, v20
	v_mov_b32_e32 v75, v20
	s_waitcnt vmcnt(0)
	v_mov_b32_e32 v28, v20
	v_mov_b32_e32 v29, v20
	v_mov_b32_e32 v30, v20
	v_mov_b32_e32 v31, v20
	v_mov_b32_e32 v32, v20
	v_mov_b32_e32 v33, v20
	v_mov_b32_e32 v34, v20
	v_mov_b32_e32 v35, v20
	v_mov_b32_e32 v44, v20
	v_mov_b32_e32 v45, v20
	v_mov_b32_e32 v46, v20
	v_mov_b32_e32 v47, v20
	v_mov_b32_e32 v48, v20
	v_mov_b32_e32 v49, v20
	v_mov_b32_e32 v50, v20
	v_mov_b32_e32 v51, v20
	v_mov_b32_e32 v60, v20
	v_mov_b32_e32 v61, v20
	v_mov_b32_e32 v62, v20
	v_mov_b32_e32 v63, v20
	v_mov_b32_e32 v64, v20
	v_mov_b32_e32 v65, v20
	v_mov_b32_e32 v66, v20
	v_mov_b32_e32 v67, v20
	v_mov_b32_e32 v76, v20
	v_mov_b32_e32 v77, v20
	v_mov_b32_e32 v78, v20
	v_mov_b32_e32 v79, v20
	v_mov_b32_e32 v80, v20
	v_mov_b32_e32 v81, v20
	v_mov_b32_e32 v82, v20
	v_mov_b32_e32 v83, v20
	v_mov_b32_e32 v84, v20
	v_mov_b32_e32 v85, v20
	v_mov_b32_e32 v86, v20
	v_mov_b32_e32 v87, v20
	v_mov_b32_e32 v88, v20
	v_mov_b32_e32 v89, v20
	v_mov_b32_e32 v90, v20
	v_mov_b32_e32 v91, v20
	v_mov_b32_e32 v100, v20
	v_mov_b32_e32 v101, v20
	v_mov_b32_e32 v102, v20
	v_mov_b32_e32 v103, v20
	v_mov_b32_e32 v104, v20
	v_mov_b32_e32 v105, v20
	v_mov_b32_e32 v106, v20
	v_mov_b32_e32 v107, v20
	v_mov_b32_e32 v116, v20
	v_mov_b32_e32 v117, v20
	v_mov_b32_e32 v118, v20
	v_mov_b32_e32 v119, v20
	v_mov_b32_e32 v120, v20
	v_mov_b32_e32 v121, v20
	v_mov_b32_e32 v122, v20
	v_mov_b32_e32 v123, v20
	v_mov_b32_e32 v132, v20
	v_mov_b32_e32 v133, v20
	v_mov_b32_e32 v134, v20
	v_mov_b32_e32 v135, v20
	v_mov_b32_e32 v136, v20
	v_mov_b32_e32 v137, v20
	v_mov_b32_e32 v138, v20
	v_mov_b32_e32 v139, v20
	v_mov_b32_e32 v92, v20
	v_mov_b32_e32 v93, v20
	v_mov_b32_e32 v94, v20
	v_mov_b32_e32 v95, v20
	v_mov_b32_e32 v96, v20
	v_mov_b32_e32 v97, v20
	v_mov_b32_e32 v98, v20
	v_mov_b32_e32 v99, v20
	v_mov_b32_e32 v108, v20
	v_mov_b32_e32 v109, v20
	v_mov_b32_e32 v110, v20
	v_mov_b32_e32 v111, v20
	v_mov_b32_e32 v112, v20
	v_mov_b32_e32 v113, v20
	v_mov_b32_e32 v114, v20
	v_mov_b32_e32 v115, v20
	v_mov_b32_e32 v124, v20
	v_mov_b32_e32 v125, v20
	v_mov_b32_e32 v126, v20
	v_mov_b32_e32 v127, v20
	v_mov_b32_e32 v128, v20
	v_mov_b32_e32 v129, v20
	v_mov_b32_e32 v130, v20
	v_mov_b32_e32 v131, v20
	v_mov_b32_e32 v140, v20
	v_mov_b32_e32 v141, v20
	v_mov_b32_e32 v142, v20
	v_mov_b32_e32 v143, v20
	v_mov_b32_e32 v144, v20
	v_mov_b32_e32 v145, v20
	v_mov_b32_e32 v146, v20
	v_mov_b32_e32 v147, v20
	.p2align 6

; __device__ __forceinline__ void phase_nsa_sw(const Params& p, u16* sm) {
;     ...
;     for (int i = 0; i < ntl; ++i) {
;       __syncthreads();
;       const int v = lst[i];
;       const u16* cK = sK + (i & 1) * 2 * 64 * LDSP;
;       const u16* cV = sV + (i & 1) * 2 * 64 * LDSP;
;       if (i == nsel) {
.Lfp15_tail:
	s_add_i32 s10, s42, 1
	v_cmp_ge_i32_e64 s[8:9], s10, v231
	s_add_i32 s83, s83, 4
	s_addk_i32 s89, 0x80
	s_and_b64 vcc, exec, s[8:9]
	s_cbranch_vccnz .LBB0_1323
	s_mov_b32 s42, s10
	v_readfirstlane_b32 s11, v192
	s_nop 3
	s_cmp_lt_u32 s11, 0x100
	s_cbranch_scc1 .LBB0_1336
	v_readlane_b32 s14, v24, s42
	v_readlane_b32 s15, v25, s42
	v_cmp_ne_u32_e32 vcc, s42, v203
	s_cmp_lt_u32 s42, 64
	s_cselect_b32 s14, s14, s15
	s_cbranch_vccz .Lfp15_park
	s_branch .Lfp15_dispatch
	s_nop 0
	s_nop 0
	s_nop 0
	s_nop 0
	s_nop 0
	s_nop 0
	s_nop 0
	s_nop 0
	s_nop 0
	s_nop 0
	s_nop 0
	s_nop 0
	s_nop 0
	s_nop 0
	s_nop 0
	.p2align 6

; template <bool MASKED>
; __device__ __forceinline__ void nsa_online_step(NsaState& st, f32x4 (&s)[2][4], unsigned vmask, bool lanevalid, const u16* sV, int fr, int fq) {
;     ...
;     tmax = fmaxf(tmax, __shfl_xor(tmax, 16));
;     tmax = fmaxf(tmax, __shfl_xor(tmax, 32));
;     const bool upd = tmax > st.m[hh] + DEFER;
;     if (__ballot(upd) != 0ull) {
;       const float mnew = upd ? tmax : st.m[hh];
;       const float alpha = __builtin_amdgcn_exp2f((st.m[hh] - mnew) * SM_C);
;       st.m[hh] = mnew;
; #pragma unroll
;       for (int dm = 0; dm < 4; ++dm) st.acc[hh][dm] *= alpha;
;       st.accL[hh] *= alpha;
;     }
.Lfp15_upd1:
	v_cndmask_b32_e64 v1, v221, v1, s[30:31]
	v_mov_b32_e32 v3, v1
	s_nop 1
	v_permlane16_swap_b32_e32 v1, v3
	s_nop 0
	v_max_f32_e32 v1, v1, v3
	v_mov_b32_e32 v3, v1
	s_nop 1
	v_permlane32_swap_b32_e32 v1, v3
	s_nop 0
	v_max_f32_e32 v1, v1, v3
	v_cmp_gt_f32_e32 vcc, v1, v168
	s_nop 1
	v_cndmask_b32_e32 v3, v235, v1, vcc
	v_sub_f32_e32 v1, v235, v3
	v_mul_f32_e32 v168, 0x3e38aa3b, v1
	v_exp_f32_e32 v168, v168
	v_mov_b32_e32 v235, v3
	s_nop 0
	v_pk_mul_f32 v[132:133], v[132:133], v[168:169] op_sel_hi:[1,0]
	v_pk_mul_f32 v[134:135], v[134:135], v[168:169] op_sel_hi:[1,0]
	v_pk_mul_f32 v[116:117], v[116:117], v[168:169] op_sel_hi:[1,0]
	v_pk_mul_f32 v[118:119], v[118:119], v[168:169] op_sel_hi:[1,0]
	v_pk_mul_f32 v[112:113], v[112:113], v[168:169] op_sel_hi:[1,0]
	v_pk_mul_f32 v[114:115], v[114:115], v[168:169] op_sel_hi:[1,0]
	v_pk_mul_f32 v[108:109], v[108:109], v[168:169] op_sel_hi:[1,0]
	v_pk_mul_f32 v[110:111], v[110:111], v[168:169] op_sel_hi:[1,0]
	v_pk_mul_f32 v[104:105], v[104:105], v[168:169] op_sel_hi:[1,0]
	v_pk_mul_f32 v[106:107], v[106:107], v[168:169] op_sel_hi:[1,0]
	s_branch .Lfp15_noupd1
	.p2align 6

; template <class Epi>
; __device__ __forceinline__ void gemm_phase(LAS unsigned char* lds, const Gemm g, const StaticOrder& S, const Epi& E) {
;     ...
;     const bool has_next = S.next(ui + 1, nxt);
;     const char* nA = has_next ? (const char*)g.A + (size_t)nxt.pm * tstep : cA; const char* nB = has_next ? (const char*)g.Bt + (size_t)nxt.pn * tstep : cB;
;     for (int t = 0; t < nt; t += 2) {
;     ...
; #pragma unroll
;     for (int a = 0; a < 2; ++a)
; #pragma unroll
;       for (int b = 0; b < 2; ++b)
; #pragma unroll
;         for (int m = 0; m < 4; ++m)
; #pragma unroll
;           for (int n = 0; n < 2; ++n) acc[a][b][m][n] = (f32x4){0.f, 0.f, 0.f, 0.f};
;     cur = nxt; cA = nA; cB = nB; ++ui;
.LBB0_1421:
	s_ashr_i32 s15, s14, 31
	v_cmp_lt_i64_e32 vcc, s[16:17], v[152:153]
	s_lshl_b64 s[16:17], s[14:15], 19
	s_add_u32 s16, s56, s16
	s_addc_u32 s17, s57, s17
	s_and_b64 s[18:19], vcc, exec
	s_cselect_b32 s15, s17, s25
	s_cselect_b32 s21, s16, s24
	s_ashr_i32 s13, s12, 31
	s_lshl_b64 s[18:19], s[12:13], 19
	s_add_u32 s18, s70, s18
	s_addc_u32 s19, s71, s19
	s_and_b64 s[28:29], vcc, exec
	s_cselect_b32 s13, s19, s27
	s_cselect_b32 s50, s18, s26
	s_add_u32 s24, s24, 0x40080
	s_addc_u32 s25, s25, 0
	s_add_u32 s51, s26, 0x100
	v_mov_b32_e32 v16, 0
	s_addc_u32 s58, s27, 0
	s_mov_b32 s59, -2
	s_waitcnt lgkmcnt(0)
	v_mov_b32_e32 v17, v16
	v_mov_b32_e32 v18, v16
	v_mov_b32_e32 v19, v16
	v_mov_b32_e32 v20, v16
	v_mov_b32_e32 v21, v16
	v_mov_b32_e32 v22, v16
	v_mov_b32_e32 v23, v16
	s_waitcnt vmcnt(0)
	v_mov_b32_e32 v32, v16
	v_mov_b32_e32 v33, v16
	v_mov_b32_e32 v34, v16
	v_mov_b32_e32 v35, v16
	v_mov_b32_e32 v36, v16
	v_mov_b32_e32 v37, v16
	v_mov_b32_e32 v38, v16
	v_mov_b32_e32 v39, v16
	v_mov_b32_e32 v48, v16
	v_mov_b32_e32 v49, v16
	v_mov_b32_e32 v50, v16
	v_mov_b32_e32 v51, v16
	v_mov_b32_e32 v52, v16
	v_mov_b32_e32 v53, v16
	v_mov_b32_e32 v54, v16
	v_mov_b32_e32 v55, v16
	v_mov_b32_e32 v64, v16
	v_mov_b32_e32 v65, v16
	v_mov_b32_e32 v66, v16
	v_mov_b32_e32 v67, v16
	v_mov_b32_e32 v68, v16
	v_mov_b32_e32 v69, v16
	v_mov_b32_e32 v70, v16
	v_mov_b32_e32 v71, v16
	v_mov_b32_e32 v24, v16
	v_mov_b32_e32 v25, v16
	v_mov_b32_e32 v26, v16
	v_mov_b32_e32 v27, v16
	v_mov_b32_e32 v28, v16
	v_mov_b32_e32 v29, v16
	v_mov_b32_e32 v30, v16
	v_mov_b32_e32 v31, v16
	v_mov_b32_e32 v40, v16
	v_mov_b32_e32 v41, v16
	v_mov_b32_e32 v42, v16
	v_mov_b32_e32 v43, v16
	v_mov_b32_e32 v44, v16
	v_mov_b32_e32 v45, v16
	v_mov_b32_e32 v46, v16
	v_mov_b32_e32 v47, v16
	v_mov_b32_e32 v56, v16
	v_mov_b32_e32 v57, v16
	v_mov_b32_e32 v58, v16
	v_mov_b32_e32 v59, v16
	v_mov_b32_e32 v60, v16
	v_mov_b32_e32 v61, v16
	v_mov_b32_e32 v62, v16
	v_mov_b32_e32 v63, v16
	v_mov_b32_e32 v72, v16
	v_mov_b32_e32 v73, v16
	v_mov_b32_e32 v74, v16
	v_mov_b32_e32 v75, v16
	v_mov_b32_e32 v76, v16
	v_mov_b32_e32 v77, v16
	v_mov_b32_e32 v78, v16
	v_mov_b32_e32 v79, v16
	v_mov_b32_e32 v80, v16
	v_mov_b32_e32 v81, v16
	v_mov_b32_e32 v82, v16
	v_mov_b32_e32 v83, v16
	v_mov_b32_e32 v84, v16
	v_mov_b32_e32 v85, v16
	v_mov_b32_e32 v86, v16
	v_mov_b32_e32 v87, v16
	v_mov_b32_e32 v96, v16
	v_mov_b32_e32 v97, v16
	v_mov_b32_e32 v98, v16
	v_mov_b32_e32 v99, v16
	v_mov_b32_e32 v100, v16
	v_mov_b32_e32 v101, v16
	v_mov_b32_e32 v102, v16
	v_mov_b32_e32 v103, v16
	v_mov_b32_e32 v112, v16
	v_mov_b32_e32 v113, v16
	v_mov_b32_e32 v114, v16
	v_mov_b32_e32 v115, v16
	v_mov_b32_e32 v116, v16
	v_mov_b32_e32 v117, v16
	v_mov_b32_e32 v118, v16
	v_mov_b32_e32 v119, v16
	v_mov_b32_e32 v128, v16
	v_mov_b32_e32 v129, v16
	v_mov_b32_e32 v130, v16
	v_mov_b32_e32 v131, v16
	v_mov_b32_e32 v132, v16
	v_mov_b32_e32 v133, v16
	v_mov_b32_e32 v134, v16
	v_mov_b32_e32 v135, v16
	v_mov_b32_e32 v88, v16
	v_mov_b32_e32 v89, v16
	v_mov_b32_e32 v90, v16
	v_mov_b32_e32 v91, v16
	v_mov_b32_e32 v92, v16
	v_mov_b32_e32 v93, v16
	v_mov_b32_e32 v94, v16
	v_mov_b32_e32 v95, v16
	v_mov_b32_e32 v104, v16
	v_mov_b32_e32 v105, v16
	v_mov_b32_e32 v106, v16
	v_mov_b32_e32 v107, v16
	v_mov_b32_e32 v108, v16
	v_mov_b32_e32 v109, v16
	v_mov_b32_e32 v110, v16
	v_mov_b32_e32 v111, v16
	v_mov_b32_e32 v120, v16
	v_mov_b32_e32 v121, v16
	v_mov_b32_e32 v122, v16
	v_mov_b32_e32 v123, v16
	v_mov_b32_e32 v124, v16
	v_mov_b32_e32 v125, v16
	v_mov_b32_e32 v126, v16
	v_mov_b32_e32 v127, v16
	v_mov_b32_e32 v136, v16
	v_mov_b32_e32 v137, v16
	v_mov_b32_e32 v138, v16
	v_mov_b32_e32 v139, v16
	v_mov_b32_e32 v140, v16
	v_mov_b32_e32 v141, v16
	v_mov_b32_e32 v142, v16
	v_mov_b32_e32 v143, v16
	.p2align 6

; template <class Epi>
; __device__ __forceinline__ void gemm_phase(LAS unsigned char* lds, const Gemm g, const StaticOrder& S, const Epi& E) {
;     ...
;     const bool has_next = S.next(ui + 1, nxt);
;     const char* nA = has_next ? (const char*)g.A + (size_t)nxt.pm * tstep : cA; const char* nB = has_next ? (const char*)g.Bt + (size_t)nxt.pn * tstep : cB;
;     for (int t = 0; t < nt; t += 2) {
;     ...
; #pragma unroll
;     for (int a = 0; a < 2; ++a)
; #pragma unroll
;       for (int b = 0; b < 2; ++b)
; #pragma unroll
;         for (int m = 0; m < 4; ++m)
; #pragma unroll
;           for (int n = 0; n < 2; ++n) acc[a][b][m][n] = (f32x4){0.f, 0.f, 0.f, 0.f};
;     cur = nxt; cA = nA; cB = nB; ++ui;
.LBB0_1500:
	s_ashr_i32 s39, s38, 31
	v_cmp_lt_i64_e32 vcc, s[40:41], v[184:185]
	s_lshl_b64 s[40:41], s[38:39], 19
	s_add_u32 s40, s54, s40
	s_addc_u32 s41, s55, s41
	s_and_b64 s[42:43], vcc, exec
	s_cselect_b32 s13, s41, s47
	s_cselect_b32 s39, s40, s46
	s_ashr_i32 s37, s36, 31
	s_lshl_b64 s[42:43], s[36:37], 19
	s_add_u32 s42, s68, s42
	s_addc_u32 s43, s69, s43
	s_and_b64 s[50:51], vcc, exec
	s_cselect_b32 s37, s43, s49
	s_cselect_b32 s89, s42, s48
	s_add_u32 s46, s46, 0x40080
	s_addc_u32 s47, s47, 0
	s_add_u32 s90, s48, 0x100
	s_waitcnt vmcnt(0)
	v_mov_b32_e32 v32, 0
	s_addc_u32 s91, s49, 0
	s_mov_b32 s92, -2
	v_mov_b32_e32 v33, v32
	v_mov_b32_e32 v34, v32
	v_mov_b32_e32 v35, v32
	v_mov_b32_e32 v64, v32
	v_mov_b32_e32 v65, v32
	v_mov_b32_e32 v66, v32
	v_mov_b32_e32 v67, v32
	v_mov_b32_e32 v20, v32
	v_mov_b32_e32 v21, v32
	v_mov_b32_e32 v22, v32
	v_mov_b32_e32 v23, v32
	v_mov_b32_e32 v48, v32
	v_mov_b32_e32 v49, v32
	v_mov_b32_e32 v50, v32
	v_mov_b32_e32 v51, v32
	v_mov_b32_e32 v16, v32
	v_mov_b32_e32 v17, v32
	v_mov_b32_e32 v18, v32
	v_mov_b32_e32 v19, v32
	v_mov_b32_e32 v52, v32
	v_mov_b32_e32 v53, v32
	v_mov_b32_e32 v54, v32
	v_mov_b32_e32 v55, v32
	v_mov_b32_e32 v40, v32
	v_mov_b32_e32 v41, v32
	v_mov_b32_e32 v42, v32
	v_mov_b32_e32 v43, v32
	v_mov_b32_e32 v72, v32
	v_mov_b32_e32 v73, v32
	v_mov_b32_e32 v74, v32
	v_mov_b32_e32 v75, v32
	v_mov_b32_e32 v36, v32
	v_mov_b32_e32 v37, v32
	v_mov_b32_e32 v38, v32
	v_mov_b32_e32 v39, v32
	v_mov_b32_e32 v68, v32
	v_mov_b32_e32 v69, v32
	v_mov_b32_e32 v70, v32
	v_mov_b32_e32 v71, v32
	v_mov_b32_e32 v28, v32
	v_mov_b32_e32 v29, v32
	v_mov_b32_e32 v30, v32
	v_mov_b32_e32 v31, v32
	v_mov_b32_e32 v56, v32
	v_mov_b32_e32 v57, v32
	v_mov_b32_e32 v58, v32
	v_mov_b32_e32 v59, v32
	v_mov_b32_e32 v24, v32
	v_mov_b32_e32 v25, v32
	v_mov_b32_e32 v26, v32
	v_mov_b32_e32 v27, v32
	v_mov_b32_e32 v60, v32
	v_mov_b32_e32 v61, v32
	v_mov_b32_e32 v62, v32
	v_mov_b32_e32 v63, v32
	v_mov_b32_e32 v44, v32
	v_mov_b32_e32 v45, v32
	v_mov_b32_e32 v46, v32
	v_mov_b32_e32 v47, v32
	v_mov_b32_e32 v76, v32
	v_mov_b32_e32 v77, v32
	v_mov_b32_e32 v78, v32
	v_mov_b32_e32 v79, v32
	v_mov_b32_e32 v96, v32
	v_mov_b32_e32 v97, v32
	v_mov_b32_e32 v98, v32
	v_mov_b32_e32 v99, v32
	v_mov_b32_e32 v140, v32
	v_mov_b32_e32 v141, v32
	v_mov_b32_e32 v142, v32
	v_mov_b32_e32 v143, v32
	v_mov_b32_e32 v80, v32
	v_mov_b32_e32 v81, v32
	v_mov_b32_e32 v82, v32
	v_mov_b32_e32 v83, v32
	v_mov_b32_e32 v112, v32
	v_mov_b32_e32 v113, v32
	v_mov_b32_e32 v114, v32
	v_mov_b32_e32 v115, v32
	v_mov_b32_e32 v84, v32
	v_mov_b32_e32 v85, v32
	v_mov_b32_e32 v86, v32
	v_mov_b32_e32 v87, v32
	v_mov_b32_e32 v116, v32
	v_mov_b32_e32 v117, v32
	v_mov_b32_e32 v118, v32
	v_mov_b32_e32 v119, v32
	v_mov_b32_e32 v104, v32
	v_mov_b32_e32 v105, v32
	v_mov_b32_e32 v106, v32
	v_mov_b32_e32 v107, v32
	v_mov_b32_e32 v168, v32
	v_mov_b32_e32 v169, v32
	v_mov_b32_e32 v170, v32
	v_mov_b32_e32 v171, v32
	v_mov_b32_e32 v100, v32
	v_mov_b32_e32 v101, v32
	v_mov_b32_e32 v102, v32
	v_mov_b32_e32 v103, v32
	v_mov_b32_e32 v164, v32
	v_mov_b32_e32 v165, v32
	v_mov_b32_e32 v166, v32
	v_mov_b32_e32 v167, v32
	v_mov_b32_e32 v88, v32
	v_mov_b32_e32 v89, v32
	v_mov_b32_e32 v90, v32
	v_mov_b32_e32 v91, v32
	v_mov_b32_e32 v120, v32
	v_mov_b32_e32 v121, v32
	v_mov_b32_e32 v122, v32
	v_mov_b32_e32 v123, v32
	v_mov_b32_e32 v92, v32
	v_mov_b32_e32 v93, v32
	v_mov_b32_e32 v94, v32
	v_mov_b32_e32 v95, v32
	v_mov_b32_e32 v124, v32
	v_mov_b32_e32 v125, v32
	v_mov_b32_e32 v126, v32
	v_mov_b32_e32 v127, v32
	v_mov_b32_e32 v108, v32
	v_mov_b32_e32 v109, v32
	v_mov_b32_e32 v110, v32
	v_mov_b32_e32 v111, v32
	v_mov_b32_e32 v172, v32
	v_mov_b32_e32 v173, v32
	v_mov_b32_e32 v174, v32
	v_mov_b32_e32 v175, v32
	.p2align 6

; template <class Epi>
; __device__ __forceinline__ void gemm_phase(LAS unsigned char* lds, const Gemm g, const StaticOrder& S, const Epi& E) {
;     ...
;     const bool has_next = S.next(ui + 1, nxt);
;     const char* nA = has_next ? (const char*)g.A + (size_t)nxt.pm * tstep : cA; const char* nB = has_next ? (const char*)g.Bt + (size_t)nxt.pn * tstep : cB;
;     for (int t = 0; t < nt; t += 2) {
;     ...
; #pragma unroll
;     for (int a = 0; a < 2; ++a)
; #pragma unroll
;       for (int b = 0; b < 2; ++b)
; #pragma unroll
;         for (int m = 0; m < 4; ++m)
; #pragma unroll
;           for (int n = 0; n < 2; ++n) acc[a][b][m][n] = (f32x4){0.f, 0.f, 0.f, 0.f};
;     cur = nxt; cA = nA; cB = nB; ++ui;
.LBB0_1648:
	s_add_u32 s16, s16, 0xb0080
	s_addc_u32 s17, s17, 0
	s_add_u32 s47, s18, 0x100
	v_mov_b32_e32 v16, 0
	s_addc_u32 s48, s19, 0
	s_mov_b32 s49, -2
	s_waitcnt lgkmcnt(0)
	v_mov_b32_e32 v17, v16
	v_mov_b32_e32 v18, v16
	v_mov_b32_e32 v19, v16
	v_mov_b32_e32 v20, v16
	v_mov_b32_e32 v21, v16
	v_mov_b32_e32 v22, v16
	v_mov_b32_e32 v23, v16
	s_waitcnt vmcnt(0)
	v_mov_b32_e32 v32, v16
	v_mov_b32_e32 v33, v16
	v_mov_b32_e32 v34, v16
	v_mov_b32_e32 v35, v16
	v_mov_b32_e32 v36, v16
	v_mov_b32_e32 v37, v16
	v_mov_b32_e32 v38, v16
	v_mov_b32_e32 v39, v16
	v_mov_b32_e32 v48, v16
	v_mov_b32_e32 v49, v16
	v_mov_b32_e32 v50, v16
	v_mov_b32_e32 v51, v16
	v_mov_b32_e32 v52, v16
	v_mov_b32_e32 v53, v16
	v_mov_b32_e32 v54, v16
	v_mov_b32_e32 v55, v16
	v_mov_b32_e32 v64, v16
	v_mov_b32_e32 v65, v16
	v_mov_b32_e32 v66, v16
	v_mov_b32_e32 v67, v16
	v_mov_b32_e32 v68, v16
	v_mov_b32_e32 v69, v16
	v_mov_b32_e32 v70, v16
	v_mov_b32_e32 v71, v16
	v_mov_b32_e32 v24, v16
	v_mov_b32_e32 v25, v16
	v_mov_b32_e32 v26, v16
	v_mov_b32_e32 v27, v16
	v_mov_b32_e32 v28, v16
	v_mov_b32_e32 v29, v16
	v_mov_b32_e32 v30, v16
	v_mov_b32_e32 v31, v16
	v_mov_b32_e32 v40, v16
	v_mov_b32_e32 v41, v16
	v_mov_b32_e32 v42, v16
	v_mov_b32_e32 v43, v16
	v_mov_b32_e32 v44, v16
	v_mov_b32_e32 v45, v16
	v_mov_b32_e32 v46, v16
	v_mov_b32_e32 v47, v16
	v_mov_b32_e32 v56, v16
	v_mov_b32_e32 v57, v16
	v_mov_b32_e32 v58, v16
	v_mov_b32_e32 v59, v16
	v_mov_b32_e32 v60, v16
	v_mov_b32_e32 v61, v16
	v_mov_b32_e32 v62, v16
	v_mov_b32_e32 v63, v16
	v_mov_b32_e32 v72, v16
	v_mov_b32_e32 v73, v16
	v_mov_b32_e32 v74, v16
	v_mov_b32_e32 v75, v16
	v_mov_b32_e32 v76, v16
	v_mov_b32_e32 v77, v16
	v_mov_b32_e32 v78, v16
	v_mov_b32_e32 v79, v16
	v_mov_b32_e32 v80, v16
	v_mov_b32_e32 v81, v16
	v_mov_b32_e32 v82, v16
	v_mov_b32_e32 v83, v16
	v_mov_b32_e32 v84, v16
	v_mov_b32_e32 v85, v16
	v_mov_b32_e32 v86, v16
	v_mov_b32_e32 v87, v16
	v_mov_b32_e32 v96, v16
	v_mov_b32_e32 v97, v16
	v_mov_b32_e32 v98, v16
	v_mov_b32_e32 v99, v16
	v_mov_b32_e32 v100, v16
	v_mov_b32_e32 v101, v16
	v_mov_b32_e32 v102, v16
	v_mov_b32_e32 v103, v16
	v_mov_b32_e32 v112, v16
	v_mov_b32_e32 v113, v16
	v_mov_b32_e32 v114, v16
	v_mov_b32_e32 v115, v16
	v_mov_b32_e32 v116, v16
	v_mov_b32_e32 v117, v16
	v_mov_b32_e32 v118, v16
	v_mov_b32_e32 v119, v16
	v_mov_b32_e32 v128, v16
	v_mov_b32_e32 v129, v16
	v_mov_b32_e32 v130, v16
	v_mov_b32_e32 v131, v16
	v_mov_b32_e32 v132, v16
	v_mov_b32_e32 v133, v16
	v_mov_b32_e32 v134, v16
	v_mov_b32_e32 v135, v16
	v_mov_b32_e32 v88, v16
	v_mov_b32_e32 v89, v16
	v_mov_b32_e32 v90, v16
	v_mov_b32_e32 v91, v16
	v_mov_b32_e32 v92, v16
	v_mov_b32_e32 v93, v16
	v_mov_b32_e32 v94, v16
	v_mov_b32_e32 v95, v16
	v_mov_b32_e32 v104, v16
	v_mov_b32_e32 v105, v16
	v_mov_b32_e32 v106, v16
	v_mov_b32_e32 v107, v16
	v_mov_b32_e32 v108, v16
	v_mov_b32_e32 v109, v16
	v_mov_b32_e32 v110, v16
	v_mov_b32_e32 v111, v16
	v_mov_b32_e32 v120, v16
	v_mov_b32_e32 v121, v16
	v_mov_b32_e32 v122, v16
	v_mov_b32_e32 v123, v16
	v_mov_b32_e32 v124, v16
	v_mov_b32_e32 v125, v16
	v_mov_b32_e32 v126, v16
	v_mov_b32_e32 v127, v16
	v_mov_b32_e32 v136, v16
	v_mov_b32_e32 v137, v16
	v_mov_b32_e32 v138, v16
	v_mov_b32_e32 v139, v16
	v_mov_b32_e32 v140, v16
	v_mov_b32_e32 v141, v16
	v_mov_b32_e32 v142, v16
	v_mov_b32_e32 v143, v16
	.p2align 6
